# prologue weight transposes: tile barrier moved below the global loads so the loads issue before the LDS hand-off
# baseline (speedup 1.0000x reference)
.LBB0_66:
	s_abs_i32 s43, s40
	s_mul_hi_u32 s44, s43, s7
	s_mul_i32 s45, s44, s8
	s_sub_i32 s43, s43, s45
	s_ashr_i32 s42, s40, 31
	s_add_i32 s46, s44, 1
	s_sub_i32 s45, s43, s8
	s_cmp_ge_u32 s43, s8
	s_cselect_b32 s44, s46, s44
	s_cselect_b32 s43, s45, s43
	s_add_i32 s45, s44, 1
	s_cmp_ge_u32 s43, s8
	s_cselect_b32 s43, s45, s44
	s_xor_b32 s43, s43, s42
	s_sub_i32 s43, s43, s42
	s_lshl_b32 s42, s43, 6
	v_add_u32_e32 v12, s42, v1
	s_mul_i32 s43, s38, s43
	v_mad_u64_u32 v[10:11], s[46:47], v12, s0, 0
	s_add_i32 s44, s41, s43
	v_ashrrev_i32_e32 v13, 31, v12
	v_add_u32_e32 v16, 32, v12
	v_mov_b32_e32 v12, v11
	s_ashr_i32 s45, s44, 31
	v_ashrrev_i32_e32 v19, 31, v16
	v_mad_u64_u32 v[16:17], s[46:47], v16, s0, 0
	v_mad_u64_u32 v[12:13], s[46:47], v13, s0, v[12:13]
	v_lshl_add_u64 v[14:15], s[44:45], 2, v[4:5]
	v_mov_b32_e32 v18, v17
	v_mov_b32_e32 v11, v12
	v_mad_u64_u32 v[12:13], s[46:47], v19, s0, v[18:19]
	v_lshl_add_u64 v[10:11], v[10:11], 2, v[14:15]
	v_mov_b32_e32 v17, v12
	global_load_dwordx4 v[10:13], v[10:11], off
	v_lshl_add_u64 v[14:15], v[16:17], 2, v[14:15]
	global_load_dwordx4 v[14:17], v[14:15], off
	v_add_u32_e32 v18, s44, v1
	v_ashrrev_i32_e32 v21, 31, v18
	v_mad_u64_u32 v[18:19], s[44:45], v18, s37, 0
	v_mov_b32_e32 v20, v19
	v_mad_u64_u32 v[20:21], s[44:45], v21, s37, v[20:21]
	v_mov_b32_e32 v19, v20
	s_ashr_i32 s43, s42, 31
	v_lshl_add_u64 v[18:19], v[18:19], 1, s[4:5]
	s_add_i32 s40, s40, s6
	s_add_i32 s41, s41, s39
	v_lshl_add_u64 v[18:19], s[42:43], 1, v[18:19]
	s_cmp_lt_i32 s40, s9
	v_lshl_add_u64 v[18:19], v[18:19], 0, v[2:3]
	s_barrier
	s_waitcnt vmcnt(1)
	ds_write2_b32 v7, v10, v11 offset1:1
	ds_write2_b32 v7, v12, v13 offset0:2 offset1:3
	s_waitcnt vmcnt(0)
	ds_write2_b32 v8, v14, v15 offset1:1
	ds_write2_b32 v9, v16, v17 offset1:1
	s_waitcnt lgkmcnt(0)
	s_barrier
	ds_read2_b32 v[10:11], v6 offset1:33
	ds_read2_b32 v[12:13], v6 offset0:66 offset1:99
	ds_read2_b32 v[14:15], v6 offset0:132 offset1:165
	ds_read2_b32 v[16:17], v6 offset0:198 offset1:231
	s_waitcnt lgkmcnt(3)
	v_cvt_pk_bf16_f32 v10, v10, v11
	s_waitcnt lgkmcnt(2)
	v_cvt_pk_bf16_f32 v11, v12, v13
	s_waitcnt lgkmcnt(1)
	v_cvt_pk_bf16_f32 v12, v14, v15
	s_waitcnt lgkmcnt(0)
	v_cvt_pk_bf16_f32 v13, v16, v17
	global_store_dwordx4 v[18:19], v[10:13], off
	s_cbranch_scc1 .LBB0_66
	s_branch .LBB0_31
